# in-projection walks tile columns in descending order so XBCP (read next by the conv phase) is the most recently written data
# speedup vs baseline: 1.0090x; 1.0002x over previous
; __device__ __forceinline__ int fresh_lane() { int l; asm volatile("v_mbcnt_lo_u32_b32 %0, -1, 0\n\tv_mbcnt_hi_u32_b32 %0, -1, %0" : "=v"(l)); return l; }
; #define PG8_STAGE(bufoff, gbase, voff) do { _Pragma("unroll") for (int _i = 0; _i < 2; ++_i) \
;         __builtin_amdgcn_global_load_lds((const unsigned*)((const char*)(gbase) + (voff)[_i]), (LAS unsigned*)(lds + (bufoff) + ldsw + _i * 8192), 16, 0, 0); } while (0)
; #define PG8_BAR __builtin_amdgcn_s_barrier()
; template <class Epi, class Sched, bool ALIGN_EPI>
; __device__ __forceinline__ void gemm_phase(LAS unsigned char* lds, const int wid, const int lda_, const int ldb_, const int K_, const Sched& S, const Epi& E) {
;     ...
;     const int lane = fresh_lane(), tid = wid * 64 + lane;
;     const int wr = wid >> 2, wc = wid & 3, fr = lane & 15, fq = lane >> 4;
;     unsigned voffA[2], voffB[2];
; #pragma unroll
;     for (int i = 0; i < 2; ++i) { int R, C; stage_rc(tid * 16 + i * 8192, R, C); const int Rb = Epi::PERM ? ((R & ~31) + perm32(R & 31)) : R;
;         voffA[i] = (unsigned)(R * lda + C) * 2u; voffB[i] = (unsigned)(Rb * ldb + C) * 2u; }
;     const size_t kstep = (size_t)(BK * 2);
;     const size_t hstepA = (size_t)HALF * lda * 2, hstepB = (size_t)HALF * ldb * 2;
;     const unsigned ldsw = (unsigned)wid * 1024u;
;     const int aoff = lds_byte(wr * 64 + fr, fq * 8), boff = lds_byte(wc * 32 + fr, fq * 8);
;     ...
;     Unit cur, nxt; int ui = 0;
;     if (!S.next(0, cur)) return;
;     f32x4 acc[2][2][4][2];
; #pragma unroll
;     for (int a = 0; a < 2; ++a)
; #pragma unroll
;         for (int b = 0; b < 2; ++b)
; #pragma unroll
;             for (int m = 0; m < 4; ++m)
; #pragma unroll
;                 for (int n = 0; n < 2; ++n) acc[a][b][m][n] = (f32x4){0.f, 0.f, 0.f, 0.f};
;     bf16x8 At[4][2], B0[2][2], B1[2][2];
;     const char* cA = S.a(cur); const char* cB = S.b(cur);
;     PG8_STAGE(PG8_SB(0, 0), cB, voffB); PG8_STAGE(PG8_SB(0, 1), cB + hstepB, voffB); PG8_STAGE(PG8_SA(0, 0), cA, voffA); PG8_STAGE(PG8_SA(0, 1), cA + hstepA, voffA);
;     if (wr == 1) PG8_BAR;
;     PG8_WAIT_V(2); PG8_BAR;
;     PG8_STAGE(PG8_SB(1, 0), cB + kstep, voffB); PG8_STAGE(PG8_SA(1, 0), cA + kstep, voffA); PG8_STAGE(PG8_SB(1, 1), cB + hstepB + kstep, voffB);
;     __device__ __forceinline__ bool next(int i, pg8::Unit& u) const {
;     ...
;         if (L < 64 * 41) { pg8::tile_of_id<41>(L, 64, u.pm, u.pn); return true; }
.LBB0_287:
	s_andn2_b64 vcc, exec, s[0:1]
	s_cbranch_vccnz .LBB0_375
	s_and_b64 s[0:1], s[28:29], exec
	s_movk_i32 s0, 0xa8
	s_cselect_b32 s6, s0, 0x148
	v_readlane_b32 s0, v252, 53
	s_cmp_lt_u32 s0, s6
	v_readlane_b32 s4, v253, 48
	s_cselect_b64 s[0:1], -1, 0
	v_readlane_b32 s5, v253, 49
	s_or_b64 s[0:1], s[4:5], s[0:1]
	s_movk_i32 s34, 0x800
	s_movk_i32 s36, 0x800
	s_andn2_b64 vcc, exec, s[0:1]
	s_waitcnt vmcnt(0)
	v_mbcnt_lo_u32_b32 v0, -1, 0
	v_mbcnt_hi_u32_b32 v0, -1, v0
	v_mbcnt_lo_u32_b32 v6, -1, 0
	v_mbcnt_hi_u32_b32 v6, -1, v6
	s_cbranch_vccnz .LBB0_316
	v_lshl_add_u32 v3, v6, 4, s3
	v_add_u32_e32 v0, 0x2000, v3
	v_readlane_b32 s0, v255, 36
	v_ashrrev_i32_e32 v1, 31, v0
	s_mul_i32 s4, s0, 0x2900000
	v_readlane_b32 s0, v252, 50
	v_lshrrev_b32_e32 v1, 22, v1
	v_readlane_b32 s1, v252, 51
	v_add_u32_e32 v1, v0, v1
	s_and_b64 s[0:1], s[0:1], s[28:29]
	v_ashrrev_i32_e32 v1, 10, v1
	s_and_b64 s[0:1], s[0:1], exec
	v_mul_i32_i24_e32 v2, 0x400, v1
	v_readlane_b32 s0, v252, 54
	v_sub_u32_e32 v0, v0, v2
	s_cselect_b32 s15, 40, s0
	s_add_u32 s0, s66, s4
	v_lshrrev_b32_e32 v2, 4, v0
	s_addc_u32 s1, s67, 0
	v_bitop3_b32 v2, v2, v0, 32 bitop3:0x6c
	s_add_u32 s7, s0, 0x2400000
	v_ashrrev_i32_e32 v0, 31, v2
	s_addc_u32 s14, s1, 0
	s_ashr_i32 s35, s34, 31
	s_ashr_i32 s37, s36, 31
	v_readlane_b32 s4, v253, 48
	v_lshrrev_b32_e32 v0, 26, v0
	s_lshl_b64 s[0:1], s[34:35], 8
	s_lshl_b64 s[10:11], s[36:37], 8
	v_readlane_b32 s5, v253, 49
	v_add_u32_e32 v4, v2, v0
	v_lshlrev_b32_e32 v5, 3, v1
	v_readlane_b32 s100, v252, 57
	s_sub_i32 s100, 40, s100
	s_and_b64 s[4:5], s[4:5], exec
	v_ashrrev_i32_e32 v0, 6, v4
	v_and_b32_e32 v5, -16, v5
	s_nop 0
	v_add_u32_e32 v5, v0, v5
	s_cselect_b32 s30, s100, s15
	v_and_b32_e32 v0, 3, v0
	s_mov_b32 s4, 0x7fffffe0
	v_lshrrev_b32_e32 v7, 2, v5
	v_lshlrev_b32_e32 v8, 1, v5
	v_and_or_b32 v0, v5, s4, v0
	v_and_b32_e32 v7, 4, v7
	v_and_b32_e32 v8, 24, v8
	v_or3_b32 v0, v0, v7, v8
	v_mul_lo_u32 v7, v0, s36
	v_lshlrev_b32_e32 v0, 5, v1
	v_and_b32_e32 v1, 0xffc0, v4
	v_sub_u32_e32 v1, v2, v1
	v_lshrrev_b16_e32 v2, 7, v1
	v_and_b32_e32 v2, 1, v2
	v_add_u16_e32 v1, v1, v2
	v_ashrrev_i16_sdwa v1, v239, sext(v1) dst_sel:DWORD dst_unused:UNUSED_PAD src0_sel:DWORD src1_sel:BYTE_0
	v_and_b32_e32 v0, 32, v0
	v_bfe_i32 v1, v1, 0, 16
	v_add_u32_e32 v4, v0, v1
	v_mul_lo_u32 v2, v5, s34
	v_add_lshl_u32 v128, v7, v4, 1
	v_add_lshl_u32 v130, v4, v2, 1
	v_ashrrev_i32_e32 v4, 31, v3
	v_lshrrev_b32_e32 v4, 22, v4
	v_add_u32_e32 v4, v3, v4
	v_ashrrev_i32_e32 v4, 10, v4
	v_mul_i32_i24_e32 v5, 0x400, v4
	v_sub_u32_e32 v3, v3, v5
	v_lshrrev_b32_e32 v5, 4, v3
	v_bitop3_b32 v5, v5, v3, 32 bitop3:0x6c
	v_ashrrev_i32_e32 v3, 31, v5
	v_lshrrev_b32_e32 v3, 26, v3
	v_add_u32_e32 v7, v5, v3
	v_lshlrev_b32_e32 v8, 3, v4
	v_ashrrev_i32_e32 v3, 6, v7
	v_and_b32_e32 v8, -16, v8
	v_add_u32_e32 v8, v3, v8
	v_and_b32_e32 v3, 3, v3
	v_lshrrev_b32_e32 v9, 2, v8
	v_lshlrev_b32_e32 v10, 1, v8
	v_and_or_b32 v3, v8, s4, v3
	v_and_b32_e32 v9, 4, v9
	v_and_b32_e32 v10, 24, v10
	v_or3_b32 v3, v3, v9, v10
	v_mul_lo_u32 v9, v3, s36
	v_lshlrev_b32_e32 v3, 5, v4
	v_and_b32_e32 v4, 0xc0, v7
	v_sub_u32_e32 v4, v5, v4
	v_ashrrev_i16_sdwa v4, v239, sext(v4) dst_sel:DWORD dst_unused:UNUSED_PAD src0_sel:DWORD src1_sel:BYTE_0
	s_ashr_i32 s31, s30, 31
	v_and_b32_e32 v3, 32, v3
	v_bfe_i32 v4, v4, 0, 16
	s_lshl_b64 s[4:5], s[30:31], 20
	v_add_u32_e32 v7, v3, v4
	s_add_u32 s48, s7, s4
	v_add_lshl_u32 v176, v9, v7, 1
	s_addc_u32 s49, s14, s5
	s_add_i32 m0, s16, 0x10000
	v_mul_lo_u32 v5, v8, s34
	global_load_lds_dwordx4 v176, s[48:49]
	s_add_i32 m0, s16, 0x12000
	s_add_u32 s4, s48, s10
	global_load_lds_dwordx4 v128, s[48:49]
	s_addc_u32 s5, s49, s11
	s_add_i32 m0, s16, 0x14000
	v_readlane_b32 s26, v253, 54
	global_load_lds_dwordx4 v176, s[4:5]
	s_add_i32 m0, s16, 0x16000
	v_add_lshl_u32 v132, v7, v5, 1
	global_load_lds_dwordx4 v128, s[4:5]
	s_mov_b32 m0, s16
	v_readlane_b32 s27, v253, 55
	s_add_i32 s15, s16, 0x2000
	s_add_u32 s34, s26, s0
	s_addc_u32 s35, s27, s1
	s_add_i32 s72, s16, 0x6000
	s_nop 0
	global_load_lds_dwordx4 v132, s[26:27]
	s_mov_b32 m0, s15
	s_nop 0
	global_load_lds_dwordx4 v130, s[26:27]
	s_add_i32 s26, s16, 0x4000
	s_mov_b32 m0, s26
	s_nop 0
	global_load_lds_dwordx4 v132, s[34:35]
	s_mov_b32 m0, s72
	s_nop 0
	global_load_lds_dwordx4 v130, s[34:35]
	v_readlane_b32 s34, v252, 58
	v_readlane_b32 s35, v252, 59
	s_andn2_b64 vcc, exec, s[34:35]
	s_cbranch_vccnz .LBB0_291
	s_barrier

;     __device__ __forceinline__ bool next(int i, pg8::Unit& u) const {
;     ...
;         if (L < 64 * 41) { pg8::tile_of_id<41>(L, 64, u.pm, u.pn); return true; }
.LBB0_296:
	s_andn2_b64 vcc, exec, s[38:39]
	s_cbranch_vccnz .LBB0_298
	s_ashr_i32 s4, s31, 31
	s_lshr_b32 s4, s4, 29
	s_add_i32 s4, s31, s4
	s_ashr_i32 s5, s4, 3
	s_and_b32 s4, s4, -8
	s_sub_i32 s4, s31, s4
	s_cmp_lt_i32 s4, 0
	s_movk_i32 s17, 0x149
	s_cselect_b32 s17, s17, 0x148
	s_mul_i32 s4, s17, s4
	s_add_i32 s4, s4, s5
	s_mul_hi_i32 s5, s4, 0x63e7063f
	s_lshr_b32 s17, s5, 31
	s_ashr_i32 s5, s5, 7
	s_add_i32 s5, s5, s17
	s_lshl_b32 s17, s5, 3
	s_mulk_i32 s5, 0x148
	s_sub_i32 s4, s4, s5
	s_bfe_u32 s5, s4, 0x3001c
	s_add_i32 s5, s4, s5
	s_sext_i32_i16 s27, s5
	s_and_b32 s5, s5, 0xfff8
	s_sub_i32 s4, s4, s5
	s_sext_i32_i16 s4, s4
	s_add_i32 s36, s17, s4
	s_ashr_i32 s34, s27, 3
	s_sub_i32 s34, 40, s34
	s_mov_b64 s[4:5], -1
